# position-DFT gemm_tile: halves share one LDS image of the common A tile and split its staging (6 instead of 8 LDS-DMA pieces per wave per step)
# baseline (speedup 1.0000x reference)
.Ldl_skipA1:
	v_mfma_f32_32x32x16_bf16 v[50:65], v[144:147], v[152:155], v[50:65]
	v_mfma_f32_32x32x16_bf16 v[34:49], v[148:151], v[152:155], v[34:49]
	v_add_u32_e32 v250, 0x5000, v86
	v_lshl_add_u64 v[248:249], v[70:71], 0, v[0:1]
	v_readfirstlane_b32 s48, v250
	v_lshl_add_u64 v[248:249], v[248:249], 0, s[22:23]
	s_mov_b32 m0, s48
	s_nop 0
	global_load_lds_dwordx4 v[248:249], off
	v_mfma_f32_32x32x16_bf16 v[18:33], v[144:147], v[156:159], v[18:33]
	v_mfma_f32_32x32x16_bf16 v[2:17], v[148:151], v[156:159], v[2:17]
	s_cmp_lg_u32 s74, 0
	s_cbranch_scc0 .Ldl_skipA2
	v_add_u32_e32 v250, 0x2000, v86
	v_subrev_u32_e32 v250, s75, v250
	v_lshl_add_u64 v[248:249], v[74:75], 0, v[0:1]
	v_readfirstlane_b32 s48, v250
	v_lshl_add_u64 v[248:249], v[248:249], 0, s[22:23]
	s_mov_b32 m0, s48
	s_nop 0
	global_load_lds_dwordx4 v[248:249], off
.Ldl_skipA2:
	v_mfma_f32_32x32x16_bf16 v[50:65], v[216:219], v[224:227], v[50:65]
	v_mfma_f32_32x32x16_bf16 v[34:49], v[220:223], v[224:227], v[34:49]
	v_add_u32_e32 v250, 0x6000, v86
	v_lshl_add_u64 v[248:249], v[66:67], 0, v[0:1]
	v_readfirstlane_b32 s48, v250
	v_lshl_add_u64 v[248:249], v[248:249], 0, s[22:23]
	s_mov_b32 m0, s48
	s_nop 0
	global_load_lds_dwordx4 v[248:249], off
	v_mfma_f32_32x32x16_bf16 v[18:33], v[216:219], v[228:231], v[18:33]
	v_mfma_f32_32x32x16_bf16 v[2:17], v[220:223], v[228:231], v[2:17]
	s_cmp_lg_u32 s74, 0
	s_cbranch_scc0 .Ldl_skipA3
	v_add_u32_e32 v250, 0x3000, v86
	v_subrev_u32_e32 v250, s75, v250
	v_lshl_add_u64 v[248:249], v[76:77], 0, v[0:1]
	v_readfirstlane_b32 s48, v250
	v_lshl_add_u64 v[248:249], v[248:249], 0, s[22:23]
	s_mov_b32 m0, s48
	s_nop 0
	global_load_lds_dwordx4 v[248:249], off
.Ldl_skipA3:
	v_mfma_f32_32x32x16_bf16 v[50:65], v[232:235], v[240:243], v[50:65]
	v_mfma_f32_32x32x16_bf16 v[34:49], v[236:239], v[240:243], v[34:49]
	v_add_u32_e32 v250, 0x7000, v86
	v_lshl_add_u64 v[248:249], v[68:69], 0, v[0:1]
	v_readfirstlane_b32 s48, v250
	v_lshl_add_u64 v[248:249], v[248:249], 0, s[22:23]
	s_mov_b32 m0, s48
	s_nop 0
	global_load_lds_dwordx4 v[248:249], off
	v_mfma_f32_32x32x16_bf16 v[18:33], v[232:235], v[244:247], v[18:33]
	v_mfma_f32_32x32x16_bf16 v[2:17], v[236:239], v[244:247], v[2:17]
	s_waitcnt vmcnt(6)
	s_barrier
	s_branch .Ldl_s1

.Ldl_skipA5:
	v_mfma_f32_32x32x16_bf16 v[50:65], v[144:147], v[152:155], v[50:65]
	v_mfma_f32_32x32x16_bf16 v[34:49], v[148:151], v[152:155], v[34:49]
	v_add_u32_e32 v250, 0xd000, v86
	v_lshl_add_u64 v[248:249], v[70:71], 0, v[0:1]
	v_readfirstlane_b32 s48, v250
	v_lshl_add_u64 v[248:249], v[248:249], 0, s[52:53]
	s_mov_b32 m0, s48
	s_nop 0
	global_load_lds_dwordx4 v[248:249], off
	v_mfma_f32_32x32x16_bf16 v[18:33], v[144:147], v[156:159], v[18:33]
	v_mfma_f32_32x32x16_bf16 v[2:17], v[148:151], v[156:159], v[2:17]
	s_cmp_lg_u32 s74, 0
	s_cbranch_scc0 .Ldl_skipA6
	v_add_u32_e32 v250, 0xa000, v86
	v_subrev_u32_e32 v250, s75, v250
	v_lshl_add_u64 v[248:249], v[74:75], 0, v[0:1]
	v_readfirstlane_b32 s48, v250
	v_lshl_add_u64 v[248:249], v[248:249], 0, s[52:53]
	s_mov_b32 m0, s48
	s_nop 0
	global_load_lds_dwordx4 v[248:249], off
.Ldl_skipA6:
	v_mfma_f32_32x32x16_bf16 v[50:65], v[216:219], v[224:227], v[50:65]
	v_mfma_f32_32x32x16_bf16 v[34:49], v[220:223], v[224:227], v[34:49]
	v_add_u32_e32 v250, 0xe000, v86
	v_lshl_add_u64 v[248:249], v[66:67], 0, v[0:1]
	v_readfirstlane_b32 s48, v250
	v_lshl_add_u64 v[248:249], v[248:249], 0, s[52:53]
	s_mov_b32 m0, s48
	s_nop 0
	global_load_lds_dwordx4 v[248:249], off
	v_mfma_f32_32x32x16_bf16 v[18:33], v[216:219], v[228:231], v[18:33]
	v_mfma_f32_32x32x16_bf16 v[2:17], v[220:223], v[228:231], v[2:17]
	s_cmp_lg_u32 s74, 0
	s_cbranch_scc0 .Ldl_skipA7
	v_add_u32_e32 v250, 0xb000, v86
	v_subrev_u32_e32 v250, s75, v250
	v_lshl_add_u64 v[248:249], v[76:77], 0, v[0:1]
	v_readfirstlane_b32 s48, v250
	v_lshl_add_u64 v[248:249], v[248:249], 0, s[52:53]
	s_mov_b32 m0, s48
	s_nop 0
	global_load_lds_dwordx4 v[248:249], off
.Ldl_skipA7:
	v_mfma_f32_32x32x16_bf16 v[50:65], v[232:235], v[240:243], v[50:65]
	v_mfma_f32_32x32x16_bf16 v[34:49], v[236:239], v[240:243], v[34:49]
	v_add_u32_e32 v250, 0xf000, v86
	v_lshl_add_u64 v[248:249], v[68:69], 0, v[0:1]
	v_readfirstlane_b32 s48, v250
	v_lshl_add_u64 v[248:249], v[248:249], 0, s[52:53]
	s_mov_b32 m0, s48
	s_nop 0
	global_load_lds_dwordx4 v[248:249], off
	v_mfma_f32_32x32x16_bf16 v[18:33], v[232:235], v[244:247], v[18:33]
	v_mfma_f32_32x32x16_bf16 v[2:17], v[236:239], v[244:247], v[2:17]
	s_waitcnt vmcnt(6)
	s_barrier
	s_branch .Ldl_next
